# grid barrier: leaders and non-leaders wait on the cross-XCD arrival counter itself (no separate release word hop)
# speedup vs baseline: 1.0042x; 1.0017x over previous
; __device__ __forceinline__ unsigned xb_ld(unsigned* p)              { return __hip_atomic_load(p, __ATOMIC_RELAXED, __HIP_MEMORY_SCOPE_AGENT); }
; __device__ __forceinline__ unsigned xb_add(unsigned* p, unsigned v) { return __hip_atomic_fetch_add(p, v, __ATOMIC_RELAXED, __HIP_MEMORY_SCOPE_AGENT); }
; #define XB_SPIN(cond, bar) do { unsigned _sp = 0; while (cond) { __builtin_amdgcn_s_sleep(1); \
;     if ((++_sp & 255u) == 0u) { if (xb_ld(&(bar)[XB_TMO])) break; if (_sp > XB_SPIN_CAP) { atomicAdd(&(bar)[XB_TMO], 1u); break; } } } } while (0)
; __device__ __forceinline__ void xcd_barrier(const XcdBarrier& b) {
;     ...
;         const unsigned old = xb_add(&bar[XB_XSUB(b.x)], 1u);
;         const unsigned gen = old / nloc;
;         if (old + 1u == (gen + 1u) * nloc) {
;             __builtin_amdgcn_fence(__ATOMIC_RELEASE, "agent");
;             asm volatile("s_waitcnt vmcnt(0)" ::: "memory");
;             const unsigned og = xb_add(&bar[XB_TOP], 1u);
;             const unsigned tg = og / nx;
;             if (og + 1u == (tg + 1u) * nx) xb_add(&bar[XB_TOPGEN], 1u);
;             else XB_SPIN(xb_ld(&bar[XB_TOPGEN]) == tg, bar);
;             __builtin_amdgcn_fence(__ATOMIC_ACQUIRE, "agent");
;             xb_add(&bar[XB_XGEN(b.x)], 1u);
;             asm volatile("s_waitcnt vmcnt(0)" ::: "memory");
;         } else {
;             XB_SPIN(xb_ld(&bar[XB_XGEN(b.x)]) == gen, bar);
;             __builtin_amdgcn_fence(__ATOMIC_ACQUIRE, "agent");
;             asm volatile("s_waitcnt vmcnt(0)" ::: "memory");
;         }
.LBB0_225:
	s_or_b64 exec, exec, s[14:15]
	v_cvt_f32_u32_e32 v4, v2
	s_waitcnt vmcnt(0)
	v_readfirstlane_b32 s2, v3
	v_sub_u32_e32 v3, 0, v2
	v_rcp_iflag_f32_e32 v4, v4
	v_add_u32_e32 v5, s2, v1
	v_mul_f32_e32 v4, 0x4f7ffffe, v4
	v_cvt_u32_f32_e32 v4, v4
	v_mul_lo_u32 v1, v3, v4
	v_mul_hi_u32 v1, v4, v1
	v_add_u32_e32 v1, v4, v1
	v_mul_hi_u32 v1, v5, v1
	v_mul_lo_u32 v3, v1, v2
	v_sub_u32_e32 v3, v5, v3
	v_add_u32_e32 v4, 1, v1
	v_sub_u32_e32 v6, v3, v2
	v_cmp_ge_u32_e32 vcc, v3, v2
	s_nop 1
	v_cndmask_b32_e32 v1, v1, v4, vcc
	v_cndmask_b32_e32 v3, v3, v6, vcc
	v_add_u32_e32 v4, 1, v1
	v_cmp_ge_u32_e32 vcc, v3, v2
	v_add_u32_e32 v3, 1, v5
	s_nop 0
	v_cndmask_b32_e32 v1, v1, v4, vcc
	v_mul_lo_u32 v4, v2, v1
	v_add_u32_e32 v2, v4, v2
	v_cmp_ne_u32_e32 vcc, v3, v2
	s_and_saveexec_b64 s[12:13], vcc
	s_xor_b64 s[12:13], exec, s[12:13]
	s_cbranch_execz .LBB0_239
	s_waitcnt lgkmcnt(0)
	v_add_u32_e32 v6, 1, v1
	v_mul_lo_u32 v6, v6, v0
	s_add_u32 s18, s6, 0x9783400
	s_addc_u32 s19, s7, 0
	global_load_dword v0, v65, s[18:19] sc1
	s_waitcnt vmcnt(0)
	v_cmp_lt_u32_e32 vcc, v0, v6
	s_and_saveexec_b64 s[14:15], vcc
	s_cbranch_execz .LBB0_238
	s_add_u32 s16, s6, 0x9780200
	s_addc_u32 s17, s7, 0
	s_mov_b32 s2, 1
	s_mov_b64 s[20:21], 0
	s_branch .LBB0_229

; __device__ __forceinline__ unsigned xb_ld(unsigned* p)              { return __hip_atomic_load(p, __ATOMIC_RELAXED, __HIP_MEMORY_SCOPE_AGENT); }
; #define XB_SPIN(cond, bar) do { unsigned _sp = 0; while (cond) { __builtin_amdgcn_s_sleep(1); \
;     if ((++_sp & 255u) == 0u) { if (xb_ld(&(bar)[XB_TMO])) break; if (_sp > XB_SPIN_CAP) { atomicAdd(&(bar)[XB_TMO], 1u); break; } } } } while (0)
; __device__ __forceinline__ void xcd_barrier(const XcdBarrier& b) {
;     ...
;             XB_SPIN(xb_ld(&bar[XB_XGEN(b.x)]) == gen, bar);
.LBB0_231:
	global_load_dword v0, v65, s[18:19] sc1
	s_add_i32 s2, s2, 1
	s_mov_b64 s[26:27], -1
	s_waitcnt vmcnt(0)
	v_cmp_ge_u32_e32 vcc, v0, v6
	s_orn2_b64 s[24:25], vcc, exec
	s_branch .LBB0_228

; __device__ __forceinline__ unsigned xb_ld(unsigned* p)              { return __hip_atomic_load(p, __ATOMIC_RELAXED, __HIP_MEMORY_SCOPE_AGENT); }
; __device__ __forceinline__ unsigned xb_add(unsigned* p, unsigned v) { return __hip_atomic_fetch_add(p, v, __ATOMIC_RELAXED, __HIP_MEMORY_SCOPE_AGENT); }
; #define XB_SPIN(cond, bar) do { unsigned _sp = 0; while (cond) { __builtin_amdgcn_s_sleep(1); \
;     if ((++_sp & 255u) == 0u) { if (xb_ld(&(bar)[XB_TMO])) break; if (_sp > XB_SPIN_CAP) { atomicAdd(&(bar)[XB_TMO], 1u); break; } } } } while (0)
; __device__ __forceinline__ void xcd_barrier(const XcdBarrier& b) {
;     ...
;         if (old + 1u == (gen + 1u) * nloc) {
;             __builtin_amdgcn_fence(__ATOMIC_RELEASE, "agent");
;             asm volatile("s_waitcnt vmcnt(0)" ::: "memory");
;             const unsigned og = xb_add(&bar[XB_TOP], 1u);
;             const unsigned tg = og / nx;
;             if (og + 1u == (tg + 1u) * nx) xb_add(&bar[XB_TOPGEN], 1u);
;             else XB_SPIN(xb_ld(&bar[XB_TOPGEN]) == tg, bar);
;             __builtin_amdgcn_fence(__ATOMIC_ACQUIRE, "agent");
.LBB0_242:
	s_or_b64 exec, exec, s[16:17]
	v_cvt_f32_u32_e32 v3, v0
	s_waitcnt vmcnt(0)
	v_readfirstlane_b32 s2, v2
	v_sub_u32_e32 v2, 0, v0
	s_add_u32 s14, s6, 0x9783500
	v_rcp_iflag_f32_e32 v3, v3
	v_add_u32_e32 v1, s2, v1
	v_add_u32_e32 v4, 1, v1
	s_addc_u32 s15, s7, 0
	v_mul_f32_e32 v3, 0x4f7ffffe, v3
	v_cvt_u32_f32_e32 v3, v3
	s_mov_b64 s[18:19], -1
	v_mul_lo_u32 v2, v2, v3
	v_mul_hi_u32 v2, v3, v2
	v_add_u32_e32 v2, v3, v2
	v_mul_hi_u32 v2, v1, v2
	v_mul_lo_u32 v3, v2, v0
	v_sub_u32_e32 v1, v1, v3
	v_add_u32_e32 v5, 1, v2
	v_sub_u32_e32 v3, v1, v0
	v_cmp_ge_u32_e32 vcc, v1, v0
	s_nop 1
	v_cndmask_b32_e32 v2, v2, v5, vcc
	v_cndmask_b32_e32 v1, v1, v3, vcc
	v_add_u32_e32 v3, 1, v2
	v_cmp_ge_u32_e32 vcc, v1, v0
	s_nop 1
	v_cndmask_b32_e32 v2, v2, v3, vcc
	v_mul_lo_u32 v1, v0, v2
	v_add_u32_e32 v0, v1, v0
	v_mov_b32_e32 v7, v0
	v_cmp_ne_u32_e32 vcc, v4, v0
	v_mov_b64_e32 v[0:1], s[14:15]
	s_and_saveexec_b64 s[16:17], vcc
	s_cbranch_execz .LBB0_254
	s_add_u32 s30, s6, 0x9783400
	s_addc_u32 s31, s7, 0
	global_load_dword v0, v65, s[30:31] sc1
	s_mov_b64 s[22:23], 0
	s_waitcnt vmcnt(0)
	v_cmp_lt_u32_e32 vcc, v0, v7
	s_and_saveexec_b64 s[20:21], vcc
	s_cbranch_execz .LBB0_253
	s_add_u32 s18, s6, 0x9780200
	s_addc_u32 s19, s7, 0
	s_mov_b32 s2, 1
	s_mov_b64 s[6:7], 0
	s_branch .LBB0_246

; __device__ __forceinline__ unsigned xb_ld(unsigned* p)              { return __hip_atomic_load(p, __ATOMIC_RELAXED, __HIP_MEMORY_SCOPE_AGENT); }
; #define XB_SPIN(cond, bar) do { unsigned _sp = 0; while (cond) { __builtin_amdgcn_s_sleep(1); \
;     if ((++_sp & 255u) == 0u) { if (xb_ld(&(bar)[XB_TMO])) break; if (_sp > XB_SPIN_CAP) { atomicAdd(&(bar)[XB_TMO], 1u); break; } } } } while (0)
; __device__ __forceinline__ void xcd_barrier(const XcdBarrier& b) {
;     ...
;             else XB_SPIN(xb_ld(&bar[XB_TOPGEN]) == tg, bar);
.LBB0_248:
	global_load_dword v0, v65, s[30:31] sc1
	s_add_i32 s2, s2, 1
	s_mov_b64 s[26:27], -1
	s_waitcnt vmcnt(0)
	v_cmp_ge_u32_e32 vcc, v0, v7
	s_orn2_b64 s[24:25], vcc, exec
	s_branch .LBB0_245

; __device__ __forceinline__ unsigned xb_ld(unsigned* p)              { return __hip_atomic_load(p, __ATOMIC_RELAXED, __HIP_MEMORY_SCOPE_AGENT); }
; __device__ __forceinline__ unsigned xb_add(unsigned* p, unsigned v) { return __hip_atomic_fetch_add(p, v, __ATOMIC_RELAXED, __HIP_MEMORY_SCOPE_AGENT); }
; #define XB_SPIN(cond, bar) do { unsigned _sp = 0; while (cond) { __builtin_amdgcn_s_sleep(1); \
;     if ((++_sp & 255u) == 0u) { if (xb_ld(&(bar)[XB_TMO])) break; if (_sp > XB_SPIN_CAP) { atomicAdd(&(bar)[XB_TMO], 1u); break; } } } } while (0)
; __device__ __forceinline__ void xcd_barrier(const XcdBarrier& b) {
;     ...
;         const unsigned old = xb_add(&bar[XB_XSUB(b.x)], 1u);
;         const unsigned gen = old / nloc;
;         if (old + 1u == (gen + 1u) * nloc) {
;             __builtin_amdgcn_fence(__ATOMIC_RELEASE, "agent");
;             asm volatile("s_waitcnt vmcnt(0)" ::: "memory");
;             const unsigned og = xb_add(&bar[XB_TOP], 1u);
;             const unsigned tg = og / nx;
;             if (og + 1u == (tg + 1u) * nx) xb_add(&bar[XB_TOPGEN], 1u);
;             else XB_SPIN(xb_ld(&bar[XB_TOPGEN]) == tg, bar);
;             __builtin_amdgcn_fence(__ATOMIC_ACQUIRE, "agent");
;             xb_add(&bar[XB_XGEN(b.x)], 1u);
;             asm volatile("s_waitcnt vmcnt(0)" ::: "memory");
;         } else {
;             XB_SPIN(xb_ld(&bar[XB_XGEN(b.x)]) == gen, bar);
;             __builtin_amdgcn_fence(__ATOMIC_ACQUIRE, "agent");
;             asm volatile("s_waitcnt vmcnt(0)" ::: "memory");
;         }
.LBB0_352:
	s_or_b64 exec, exec, s[12:13]
	v_cvt_f32_u32_e32 v4, v2
	s_waitcnt vmcnt(0)
	v_readfirstlane_b32 s2, v3
	v_sub_u32_e32 v3, 0, v2
	v_rcp_iflag_f32_e32 v4, v4
	v_add_u32_e32 v5, s2, v1
	v_mul_f32_e32 v4, 0x4f7ffffe, v4
	v_cvt_u32_f32_e32 v4, v4
	v_mul_lo_u32 v1, v3, v4
	v_mul_hi_u32 v1, v4, v1
	v_add_u32_e32 v1, v4, v1
	v_mul_hi_u32 v1, v5, v1
	v_mul_lo_u32 v3, v1, v2
	v_sub_u32_e32 v3, v5, v3
	v_add_u32_e32 v4, 1, v1
	v_cmp_ge_u32_e32 vcc, v3, v2
	s_nop 1
	v_cndmask_b32_e32 v1, v1, v4, vcc
	v_sub_u32_e32 v4, v3, v2
	v_cndmask_b32_e32 v3, v3, v4, vcc
	v_add_u32_e32 v4, 1, v1
	v_cmp_ge_u32_e32 vcc, v3, v2
	v_add_u32_e32 v3, 1, v5
	s_nop 0
	v_cndmask_b32_e32 v1, v1, v4, vcc
	v_mul_lo_u32 v4, v2, v1
	v_add_u32_e32 v2, v4, v2
	v_cmp_ne_u32_e32 vcc, v3, v2
	s_and_saveexec_b64 s[10:11], vcc
	s_xor_b64 s[10:11], exec, s[10:11]
	s_cbranch_execz .LBB0_366
	s_waitcnt lgkmcnt(0)
	v_add_u32_e32 v6, 1, v1
	v_mul_lo_u32 v6, v6, v0
	s_add_u32 s16, s6, 0x9783400
	s_addc_u32 s17, s7, 0
	global_load_dword v0, v65, s[16:17] sc1
	s_waitcnt vmcnt(0)
	v_cmp_lt_u32_e32 vcc, v0, v6
	s_and_saveexec_b64 s[12:13], vcc
	s_cbranch_execz .LBB0_365
	s_add_u32 s14, s6, 0x9780200
	s_addc_u32 s15, s7, 0
	s_mov_b32 s2, 1
	s_mov_b64 s[18:19], 0
	s_branch .LBB0_356

; __device__ __forceinline__ unsigned xb_ld(unsigned* p)              { return __hip_atomic_load(p, __ATOMIC_RELAXED, __HIP_MEMORY_SCOPE_AGENT); }
; #define XB_SPIN(cond, bar) do { unsigned _sp = 0; while (cond) { __builtin_amdgcn_s_sleep(1); \
;     if ((++_sp & 255u) == 0u) { if (xb_ld(&(bar)[XB_TMO])) break; if (_sp > XB_SPIN_CAP) { atomicAdd(&(bar)[XB_TMO], 1u); break; } } } } while (0)
; __device__ __forceinline__ void xcd_barrier(const XcdBarrier& b) {
;     ...
;             XB_SPIN(xb_ld(&bar[XB_XGEN(b.x)]) == gen, bar);
.LBB0_358:
	global_load_dword v0, v65, s[16:17] sc1
	s_add_i32 s2, s2, 1
	s_mov_b64 s[24:25], -1
	s_waitcnt vmcnt(0)
	v_cmp_ge_u32_e32 vcc, v0, v6
	s_orn2_b64 s[22:23], vcc, exec
	s_branch .LBB0_355

; __device__ __forceinline__ unsigned xb_ld(unsigned* p)              { return __hip_atomic_load(p, __ATOMIC_RELAXED, __HIP_MEMORY_SCOPE_AGENT); }
; __device__ __forceinline__ unsigned xb_add(unsigned* p, unsigned v) { return __hip_atomic_fetch_add(p, v, __ATOMIC_RELAXED, __HIP_MEMORY_SCOPE_AGENT); }
; #define XB_SPIN(cond, bar) do { unsigned _sp = 0; while (cond) { __builtin_amdgcn_s_sleep(1); \
;     if ((++_sp & 255u) == 0u) { if (xb_ld(&(bar)[XB_TMO])) break; if (_sp > XB_SPIN_CAP) { atomicAdd(&(bar)[XB_TMO], 1u); break; } } } } while (0)
; __device__ __forceinline__ void xcd_barrier(const XcdBarrier& b) {
;     ...
;         if (old + 1u == (gen + 1u) * nloc) {
;             __builtin_amdgcn_fence(__ATOMIC_RELEASE, "agent");
;             asm volatile("s_waitcnt vmcnt(0)" ::: "memory");
;             const unsigned og = xb_add(&bar[XB_TOP], 1u);
;             const unsigned tg = og / nx;
;             if (og + 1u == (tg + 1u) * nx) xb_add(&bar[XB_TOPGEN], 1u);
;             else XB_SPIN(xb_ld(&bar[XB_TOPGEN]) == tg, bar);
;             __builtin_amdgcn_fence(__ATOMIC_ACQUIRE, "agent");
.LBB0_369:
	s_or_b64 exec, exec, s[14:15]
	s_waitcnt vmcnt(0)
	v_readfirstlane_b32 s2, v2
	v_cvt_f32_u32_e32 v2, v0
	v_sub_u32_e32 v3, 0, v0
	v_add_u32_e32 v1, s2, v1
	s_add_u32 s12, s6, 0x9783500
	v_rcp_iflag_f32_e32 v2, v2
	s_addc_u32 s13, s7, 0
	s_mov_b64 s[16:17], -1
	v_mul_f32_e32 v2, 0x4f7ffffe, v2
	v_cvt_u32_f32_e32 v2, v2
	v_mul_lo_u32 v3, v3, v2
	v_mul_hi_u32 v3, v2, v3
	v_add_u32_e32 v2, v2, v3
	v_mul_hi_u32 v2, v1, v2
	v_mul_lo_u32 v3, v2, v0
	v_sub_u32_e32 v3, v1, v3
	v_cmp_ge_u32_e32 vcc, v3, v0
	v_add_u32_e32 v4, 1, v2
	v_add_u32_e32 v1, 1, v1
	v_cndmask_b32_e32 v2, v2, v4, vcc
	v_sub_u32_e32 v4, v3, v0
	v_cndmask_b32_e32 v3, v3, v4, vcc
	v_cmp_ge_u32_e32 vcc, v3, v0
	v_add_u32_e32 v3, 1, v2
	s_nop 0
	v_cndmask_b32_e32 v2, v2, v3, vcc
	v_mul_lo_u32 v3, v0, v2
	v_add_u32_e32 v0, v3, v0
	v_mov_b32_e32 v7, v0
	v_cmp_ne_u32_e32 vcc, v1, v0
	v_mov_b64_e32 v[0:1], s[12:13]
	s_and_saveexec_b64 s[14:15], vcc
	s_cbranch_execz .LBB0_381
	s_add_u32 s30, s6, 0x9783400
	s_addc_u32 s31, s7, 0
	global_load_dword v0, v65, s[30:31] sc1
	s_mov_b64 s[20:21], 0
	s_waitcnt vmcnt(0)
	v_cmp_lt_u32_e32 vcc, v0, v7
	s_and_saveexec_b64 s[18:19], vcc
	s_cbranch_execz .LBB0_380
	s_add_u32 s16, s6, 0x9780200
	s_addc_u32 s17, s7, 0
	s_mov_b32 s2, 1
	s_mov_b64 s[6:7], 0
	s_branch .LBB0_373

; __device__ __forceinline__ unsigned xb_ld(unsigned* p)              { return __hip_atomic_load(p, __ATOMIC_RELAXED, __HIP_MEMORY_SCOPE_AGENT); }
; #define XB_SPIN(cond, bar) do { unsigned _sp = 0; while (cond) { __builtin_amdgcn_s_sleep(1); \
;     if ((++_sp & 255u) == 0u) { if (xb_ld(&(bar)[XB_TMO])) break; if (_sp > XB_SPIN_CAP) { atomicAdd(&(bar)[XB_TMO], 1u); break; } } } } while (0)
; __device__ __forceinline__ void xcd_barrier(const XcdBarrier& b) {
;     ...
;             else XB_SPIN(xb_ld(&bar[XB_TOPGEN]) == tg, bar);
.LBB0_375:
	global_load_dword v0, v65, s[30:31] sc1
	s_add_i32 s2, s2, 1
	s_mov_b64 s[24:25], -1
	s_waitcnt vmcnt(0)
	v_cmp_ge_u32_e32 vcc, v0, v7
	s_orn2_b64 s[22:23], vcc, exec
	s_branch .LBB0_372

; __device__ __forceinline__ unsigned xb_ld(unsigned* p)              { return __hip_atomic_load(p, __ATOMIC_RELAXED, __HIP_MEMORY_SCOPE_AGENT); }
; __device__ __forceinline__ unsigned xb_add(unsigned* p, unsigned v) { return __hip_atomic_fetch_add(p, v, __ATOMIC_RELAXED, __HIP_MEMORY_SCOPE_AGENT); }
; #define XB_SPIN(cond, bar) do { unsigned _sp = 0; while (cond) { __builtin_amdgcn_s_sleep(1); \
;     if ((++_sp & 255u) == 0u) { if (xb_ld(&(bar)[XB_TMO])) break; if (_sp > XB_SPIN_CAP) { atomicAdd(&(bar)[XB_TMO], 1u); break; } } } } while (0)
; __device__ __forceinline__ void xcd_barrier(const XcdBarrier& b) {
;     ...
;         const unsigned old = xb_add(&bar[XB_XSUB(b.x)], 1u);
;         const unsigned gen = old / nloc;
;         if (old + 1u == (gen + 1u) * nloc) {
;             __builtin_amdgcn_fence(__ATOMIC_RELEASE, "agent");
;             asm volatile("s_waitcnt vmcnt(0)" ::: "memory");
;             const unsigned og = xb_add(&bar[XB_TOP], 1u);
;             const unsigned tg = og / nx;
;             if (og + 1u == (tg + 1u) * nx) xb_add(&bar[XB_TOPGEN], 1u);
;             else XB_SPIN(xb_ld(&bar[XB_TOPGEN]) == tg, bar);
;             __builtin_amdgcn_fence(__ATOMIC_ACQUIRE, "agent");
;             xb_add(&bar[XB_XGEN(b.x)], 1u);
;             asm volatile("s_waitcnt vmcnt(0)" ::: "memory");
;         } else {
;             XB_SPIN(xb_ld(&bar[XB_XGEN(b.x)]) == gen, bar);
;             __builtin_amdgcn_fence(__ATOMIC_ACQUIRE, "agent");
;             asm volatile("s_waitcnt vmcnt(0)" ::: "memory");
;         }
.LBB0_482:
	s_or_b64 exec, exec, s[14:15]
	v_cvt_f32_u32_e32 v4, v2
	s_waitcnt vmcnt(0)
	v_readfirstlane_b32 s2, v3
	v_sub_u32_e32 v3, 0, v2
	v_rcp_iflag_f32_e32 v4, v4
	v_add_u32_e32 v5, s2, v1
	v_mul_f32_e32 v4, 0x4f7ffffe, v4
	v_cvt_u32_f32_e32 v4, v4
	v_mul_lo_u32 v1, v3, v4
	v_mul_hi_u32 v1, v4, v1
	v_add_u32_e32 v1, v4, v1
	v_mul_hi_u32 v1, v5, v1
	v_mul_lo_u32 v3, v1, v2
	v_sub_u32_e32 v3, v5, v3
	v_add_u32_e32 v4, 1, v1
	v_cmp_ge_u32_e32 vcc, v3, v2
	s_nop 1
	v_cndmask_b32_e32 v1, v1, v4, vcc
	v_sub_u32_e32 v4, v3, v2
	v_cndmask_b32_e32 v3, v3, v4, vcc
	v_add_u32_e32 v4, 1, v1
	v_cmp_ge_u32_e32 vcc, v3, v2
	v_add_u32_e32 v3, 1, v5
	s_nop 0
	v_cndmask_b32_e32 v1, v1, v4, vcc
	v_mul_lo_u32 v4, v2, v1
	v_add_u32_e32 v2, v4, v2
	v_cmp_ne_u32_e32 vcc, v3, v2
	s_and_saveexec_b64 s[12:13], vcc
	s_xor_b64 s[12:13], exec, s[12:13]
	s_cbranch_execz .LBB0_496
	s_waitcnt lgkmcnt(0)
	v_add_u32_e32 v6, 1, v1
	v_mul_lo_u32 v6, v6, v0
	s_add_u32 s18, s6, 0x9783400
	s_addc_u32 s19, s7, 0
	global_load_dword v0, v65, s[18:19] sc1
	s_waitcnt vmcnt(0)
	v_cmp_lt_u32_e32 vcc, v0, v6
	s_and_saveexec_b64 s[14:15], vcc
	s_cbranch_execz .LBB0_495
	s_add_u32 s16, s6, 0x9780200
	s_addc_u32 s17, s7, 0
	s_mov_b32 s2, 1
	s_mov_b64 s[20:21], 0
	s_branch .LBB0_486

; __device__ __forceinline__ unsigned xb_ld(unsigned* p)              { return __hip_atomic_load(p, __ATOMIC_RELAXED, __HIP_MEMORY_SCOPE_AGENT); }
; __device__ __forceinline__ unsigned xb_add(unsigned* p, unsigned v) { return __hip_atomic_fetch_add(p, v, __ATOMIC_RELAXED, __HIP_MEMORY_SCOPE_AGENT); }
; #define XB_SPIN(cond, bar) do { unsigned _sp = 0; while (cond) { __builtin_amdgcn_s_sleep(1); \
;     if ((++_sp & 255u) == 0u) { if (xb_ld(&(bar)[XB_TMO])) break; if (_sp > XB_SPIN_CAP) { atomicAdd(&(bar)[XB_TMO], 1u); break; } } } } while (0)
; __device__ __forceinline__ void xcd_barrier(const XcdBarrier& b) {
;     ...
;         if (old + 1u == (gen + 1u) * nloc) {
;             __builtin_amdgcn_fence(__ATOMIC_RELEASE, "agent");
;             asm volatile("s_waitcnt vmcnt(0)" ::: "memory");
;             const unsigned og = xb_add(&bar[XB_TOP], 1u);
;             const unsigned tg = og / nx;
;             if (og + 1u == (tg + 1u) * nx) xb_add(&bar[XB_TOPGEN], 1u);
;             else XB_SPIN(xb_ld(&bar[XB_TOPGEN]) == tg, bar);
;             __builtin_amdgcn_fence(__ATOMIC_ACQUIRE, "agent");
.LBB0_499:
	s_or_b64 exec, exec, s[16:17]
	s_waitcnt vmcnt(0)
	v_readfirstlane_b32 s2, v2
	v_cvt_f32_u32_e32 v2, v0
	v_sub_u32_e32 v3, 0, v0
	v_add_u32_e32 v1, s2, v1
	s_add_u32 s14, s6, 0x9783500
	v_rcp_iflag_f32_e32 v2, v2
	s_addc_u32 s15, s7, 0
	s_mov_b64 s[18:19], -1
	v_mul_f32_e32 v2, 0x4f7ffffe, v2
	v_cvt_u32_f32_e32 v2, v2
	v_mul_lo_u32 v3, v3, v2
	v_mul_hi_u32 v3, v2, v3
	v_add_u32_e32 v2, v2, v3
	v_mul_hi_u32 v2, v1, v2
	v_mul_lo_u32 v3, v2, v0
	v_sub_u32_e32 v3, v1, v3
	v_cmp_ge_u32_e32 vcc, v3, v0
	v_add_u32_e32 v4, 1, v2
	v_add_u32_e32 v1, 1, v1
	v_cndmask_b32_e32 v2, v2, v4, vcc
	v_sub_u32_e32 v4, v3, v0
	v_cndmask_b32_e32 v3, v3, v4, vcc
	v_cmp_ge_u32_e32 vcc, v3, v0
	v_add_u32_e32 v3, 1, v2
	s_nop 0
	v_cndmask_b32_e32 v2, v2, v3, vcc
	v_mul_lo_u32 v3, v0, v2
	v_add_u32_e32 v0, v3, v0
	v_mov_b32_e32 v7, v0
	v_cmp_ne_u32_e32 vcc, v1, v0
	v_mov_b64_e32 v[0:1], s[14:15]
	s_and_saveexec_b64 s[16:17], vcc
	s_cbranch_execz .LBB0_511
	s_add_u32 s30, s6, 0x9783400
	s_addc_u32 s31, s7, 0
	global_load_dword v0, v65, s[30:31] sc1
	s_mov_b64 s[22:23], 0
	s_waitcnt vmcnt(0)
	v_cmp_lt_u32_e32 vcc, v0, v7
	s_and_saveexec_b64 s[20:21], vcc
	s_cbranch_execz .LBB0_510
	s_add_u32 s18, s6, 0x9780200
	s_addc_u32 s19, s7, 0
	s_mov_b32 s2, 1
	s_mov_b64 s[6:7], 0
	s_branch .LBB0_503

; __device__ __forceinline__ unsigned xb_ld(unsigned* p)              { return __hip_atomic_load(p, __ATOMIC_RELAXED, __HIP_MEMORY_SCOPE_AGENT); }
; __device__ __forceinline__ unsigned xb_add(unsigned* p, unsigned v) { return __hip_atomic_fetch_add(p, v, __ATOMIC_RELAXED, __HIP_MEMORY_SCOPE_AGENT); }
; #define XB_SPIN(cond, bar) do { unsigned _sp = 0; while (cond) { __builtin_amdgcn_s_sleep(1); \
;     if ((++_sp & 255u) == 0u) { if (xb_ld(&(bar)[XB_TMO])) break; if (_sp > XB_SPIN_CAP) { atomicAdd(&(bar)[XB_TMO], 1u); break; } } } } while (0)
; __device__ __forceinline__ void xcd_barrier(const XcdBarrier& b) {
;     ...
;         const unsigned old = xb_add(&bar[XB_XSUB(b.x)], 1u);
;         const unsigned gen = old / nloc;
;         if (old + 1u == (gen + 1u) * nloc) {
;             __builtin_amdgcn_fence(__ATOMIC_RELEASE, "agent");
;             asm volatile("s_waitcnt vmcnt(0)" ::: "memory");
;             const unsigned og = xb_add(&bar[XB_TOP], 1u);
;             const unsigned tg = og / nx;
;             if (og + 1u == (tg + 1u) * nx) xb_add(&bar[XB_TOPGEN], 1u);
;             else XB_SPIN(xb_ld(&bar[XB_TOPGEN]) == tg, bar);
;             __builtin_amdgcn_fence(__ATOMIC_ACQUIRE, "agent");
;             xb_add(&bar[XB_XGEN(b.x)], 1u);
;             asm volatile("s_waitcnt vmcnt(0)" ::: "memory");
;         } else {
;             XB_SPIN(xb_ld(&bar[XB_XGEN(b.x)]) == gen, bar);
;             __builtin_amdgcn_fence(__ATOMIC_ACQUIRE, "agent");
;             asm volatile("s_waitcnt vmcnt(0)" ::: "memory");
;         }
.LBB0_944:
	s_or_b64 exec, exec, s[12:13]
	v_cvt_f32_u32_e32 v4, v2
	s_waitcnt vmcnt(0)
	v_readfirstlane_b32 s2, v3
	v_sub_u32_e32 v3, 0, v2
	v_rcp_iflag_f32_e32 v4, v4
	v_add_u32_e32 v5, s2, v1
	v_mul_f32_e32 v4, 0x4f7ffffe, v4
	v_cvt_u32_f32_e32 v4, v4
	v_mul_lo_u32 v1, v3, v4
	v_mul_hi_u32 v1, v4, v1
	v_add_u32_e32 v1, v4, v1
	v_mul_hi_u32 v1, v5, v1
	v_mul_lo_u32 v3, v1, v2
	v_sub_u32_e32 v3, v5, v3
	v_add_u32_e32 v4, 1, v1
	v_cmp_ge_u32_e32 vcc, v3, v2
	s_nop 1
	v_cndmask_b32_e32 v1, v1, v4, vcc
	v_sub_u32_e32 v4, v3, v2
	v_cndmask_b32_e32 v3, v3, v4, vcc
	v_add_u32_e32 v4, 1, v1
	v_cmp_ge_u32_e32 vcc, v3, v2
	v_add_u32_e32 v3, 1, v5
	s_nop 0
	v_cndmask_b32_e32 v1, v1, v4, vcc
	v_mul_lo_u32 v4, v2, v1
	v_add_u32_e32 v2, v4, v2
	v_cmp_ne_u32_e32 vcc, v3, v2
	s_and_saveexec_b64 s[10:11], vcc
	s_xor_b64 s[10:11], exec, s[10:11]
	s_cbranch_execz .LBB0_958
	s_waitcnt lgkmcnt(0)
	v_add_u32_e32 v6, 1, v1
	v_mul_lo_u32 v6, v6, v0
	s_add_u32 s18, s6, 0x9783400
	s_addc_u32 s19, s7, 0
	global_load_dword v0, v65, s[18:19] sc1
	s_waitcnt vmcnt(0)
	v_cmp_lt_u32_e32 vcc, v0, v6
	s_and_saveexec_b64 s[12:13], vcc
	s_cbranch_execz .LBB0_957
	s_add_u32 s14, s6, 0x9780200
	s_addc_u32 s15, s7, 0
	s_mov_b32 s2, 1
	s_mov_b64 s[20:21], 0
	s_branch .LBB0_948

; __device__ __forceinline__ unsigned xb_ld(unsigned* p)              { return __hip_atomic_load(p, __ATOMIC_RELAXED, __HIP_MEMORY_SCOPE_AGENT); }
; __device__ __forceinline__ unsigned xb_add(unsigned* p, unsigned v) { return __hip_atomic_fetch_add(p, v, __ATOMIC_RELAXED, __HIP_MEMORY_SCOPE_AGENT); }
; #define XB_SPIN(cond, bar) do { unsigned _sp = 0; while (cond) { __builtin_amdgcn_s_sleep(1); \
;     if ((++_sp & 255u) == 0u) { if (xb_ld(&(bar)[XB_TMO])) break; if (_sp > XB_SPIN_CAP) { atomicAdd(&(bar)[XB_TMO], 1u); break; } } } } while (0)
; __device__ __forceinline__ void xcd_barrier(const XcdBarrier& b) {
;     ...
;         if (old + 1u == (gen + 1u) * nloc) {
;             __builtin_amdgcn_fence(__ATOMIC_RELEASE, "agent");
;             asm volatile("s_waitcnt vmcnt(0)" ::: "memory");
;             const unsigned og = xb_add(&bar[XB_TOP], 1u);
;             const unsigned tg = og / nx;
;             if (og + 1u == (tg + 1u) * nx) xb_add(&bar[XB_TOPGEN], 1u);
;             else XB_SPIN(xb_ld(&bar[XB_TOPGEN]) == tg, bar);
;             __builtin_amdgcn_fence(__ATOMIC_ACQUIRE, "agent");
.LBB0_961:
	s_or_b64 exec, exec, s[14:15]
	s_waitcnt vmcnt(0)
	v_readfirstlane_b32 s2, v2
	v_cvt_f32_u32_e32 v2, v0
	v_sub_u32_e32 v3, 0, v0
	v_add_u32_e32 v1, s2, v1
	s_add_u32 s12, s6, 0x9783500
	v_rcp_iflag_f32_e32 v2, v2
	s_addc_u32 s13, s7, 0
	s_mov_b64 s[18:19], -1
	v_mul_f32_e32 v2, 0x4f7ffffe, v2
	v_cvt_u32_f32_e32 v2, v2
	v_mul_lo_u32 v3, v3, v2
	v_mul_hi_u32 v3, v2, v3
	v_add_u32_e32 v2, v2, v3
	v_mul_hi_u32 v2, v1, v2
	v_mul_lo_u32 v3, v2, v0
	v_sub_u32_e32 v3, v1, v3
	v_cmp_ge_u32_e32 vcc, v3, v0
	v_add_u32_e32 v4, 1, v2
	v_add_u32_e32 v1, 1, v1
	v_cndmask_b32_e32 v2, v2, v4, vcc
	v_sub_u32_e32 v4, v3, v0
	v_cndmask_b32_e32 v3, v3, v4, vcc
	v_cmp_ge_u32_e32 vcc, v3, v0
	v_add_u32_e32 v3, 1, v2
	s_nop 0
	v_cndmask_b32_e32 v2, v2, v3, vcc
	v_mul_lo_u32 v3, v0, v2
	v_add_u32_e32 v0, v3, v0
	v_mov_b32_e32 v7, v0
	v_cmp_ne_u32_e32 vcc, v1, v0
	v_mov_b64_e32 v[0:1], s[12:13]
	s_and_saveexec_b64 s[14:15], vcc
	s_cbranch_execz .LBB0_973
	s_add_u32 s30, s6, 0x9783400
	s_addc_u32 s31, s7, 0
	global_load_dword v0, v65, s[30:31] sc1
	s_mov_b64 s[22:23], 0
	s_waitcnt vmcnt(0)
	v_cmp_lt_u32_e32 vcc, v0, v7
	s_and_saveexec_b64 s[20:21], vcc
	s_cbranch_execz .LBB0_972
	s_add_u32 s18, s6, 0x9780200
	s_addc_u32 s19, s7, 0
	s_mov_b32 s2, 1
	s_mov_b64 s[6:7], 0
	s_branch .LBB0_965

; __device__ __forceinline__ unsigned xb_ld(unsigned* p)              { return __hip_atomic_load(p, __ATOMIC_RELAXED, __HIP_MEMORY_SCOPE_AGENT); }
; __device__ __forceinline__ unsigned xb_add(unsigned* p, unsigned v) { return __hip_atomic_fetch_add(p, v, __ATOMIC_RELAXED, __HIP_MEMORY_SCOPE_AGENT); }
; #define XB_SPIN(cond, bar) do { unsigned _sp = 0; while (cond) { __builtin_amdgcn_s_sleep(1); \
;     if ((++_sp & 255u) == 0u) { if (xb_ld(&(bar)[XB_TMO])) break; if (_sp > XB_SPIN_CAP) { atomicAdd(&(bar)[XB_TMO], 1u); break; } } } } while (0)
; __device__ __forceinline__ void xcd_barrier(const XcdBarrier& b) {
;     ...
;         const unsigned old = xb_add(&bar[XB_XSUB(b.x)], 1u);
;         const unsigned gen = old / nloc;
;         if (old + 1u == (gen + 1u) * nloc) {
;             __builtin_amdgcn_fence(__ATOMIC_RELEASE, "agent");
;             asm volatile("s_waitcnt vmcnt(0)" ::: "memory");
;             const unsigned og = xb_add(&bar[XB_TOP], 1u);
;             const unsigned tg = og / nx;
;             if (og + 1u == (tg + 1u) * nx) xb_add(&bar[XB_TOPGEN], 1u);
;             else XB_SPIN(xb_ld(&bar[XB_TOPGEN]) == tg, bar);
;             __builtin_amdgcn_fence(__ATOMIC_ACQUIRE, "agent");
;             xb_add(&bar[XB_XGEN(b.x)], 1u);
;             asm volatile("s_waitcnt vmcnt(0)" ::: "memory");
;         } else {
;             XB_SPIN(xb_ld(&bar[XB_XGEN(b.x)]) == gen, bar);
;             __builtin_amdgcn_fence(__ATOMIC_ACQUIRE, "agent");
;             asm volatile("s_waitcnt vmcnt(0)" ::: "memory");
;         }
.LBB0_1000:
	s_or_b64 exec, exec, s[14:15]
	v_cvt_f32_u32_e32 v4, v2
	s_waitcnt vmcnt(0)
	v_readfirstlane_b32 s2, v3
	v_sub_u32_e32 v3, 0, v2
	v_rcp_iflag_f32_e32 v4, v4
	v_add_u32_e32 v5, s2, v1
	v_mul_f32_e32 v4, 0x4f7ffffe, v4
	v_cvt_u32_f32_e32 v4, v4
	v_mul_lo_u32 v1, v3, v4
	v_mul_hi_u32 v1, v4, v1
	v_add_u32_e32 v1, v4, v1
	v_mul_hi_u32 v1, v5, v1
	v_mul_lo_u32 v3, v1, v2
	v_sub_u32_e32 v3, v5, v3
	v_add_u32_e32 v4, 1, v1
	v_cmp_ge_u32_e32 vcc, v3, v2
	s_nop 1
	v_cndmask_b32_e32 v1, v1, v4, vcc
	v_sub_u32_e32 v4, v3, v2
	v_cndmask_b32_e32 v3, v3, v4, vcc
	v_add_u32_e32 v4, 1, v1
	v_cmp_ge_u32_e32 vcc, v3, v2
	v_add_u32_e32 v3, 1, v5
	s_nop 0
	v_cndmask_b32_e32 v1, v1, v4, vcc
	v_mul_lo_u32 v4, v2, v1
	v_add_u32_e32 v2, v4, v2
	v_cmp_ne_u32_e32 vcc, v3, v2
	s_and_saveexec_b64 s[12:13], vcc
	s_xor_b64 s[12:13], exec, s[12:13]
	s_cbranch_execz .LBB0_1014
	s_waitcnt lgkmcnt(0)
	v_add_u32_e32 v6, 1, v1
	v_mul_lo_u32 v6, v6, v0
	s_add_u32 s20, s4, 0x9783400
	s_addc_u32 s21, s5, 0
	global_load_dword v0, v65, s[20:21] sc1
	s_waitcnt vmcnt(0)
	v_cmp_lt_u32_e32 vcc, v0, v6
	s_and_saveexec_b64 s[14:15], vcc
	s_cbranch_execz .LBB0_1013
	s_add_u32 s18, s4, 0x9780200
	s_addc_u32 s19, s5, 0
	s_mov_b32 s2, 1
	s_mov_b64 s[22:23], 0
	s_branch .LBB0_1004

; __device__ __forceinline__ unsigned xb_ld(unsigned* p)              { return __hip_atomic_load(p, __ATOMIC_RELAXED, __HIP_MEMORY_SCOPE_AGENT); }
; #define XB_SPIN(cond, bar) do { unsigned _sp = 0; while (cond) { __builtin_amdgcn_s_sleep(1); \
;     if ((++_sp & 255u) == 0u) { if (xb_ld(&(bar)[XB_TMO])) break; if (_sp > XB_SPIN_CAP) { atomicAdd(&(bar)[XB_TMO], 1u); break; } } } } while (0)
; __device__ __forceinline__ void xcd_barrier(const XcdBarrier& b) {
;     ...
;             XB_SPIN(xb_ld(&bar[XB_XGEN(b.x)]) == gen, bar);
.LBB0_1006:
	global_load_dword v0, v65, s[20:21] sc1
	s_add_i32 s2, s2, 1
	s_mov_b64 s[28:29], -1
	s_waitcnt vmcnt(0)
	v_cmp_ge_u32_e32 vcc, v0, v6
	s_orn2_b64 s[26:27], vcc, exec
	s_branch .LBB0_1003

; __device__ __forceinline__ unsigned xb_ld(unsigned* p)              { return __hip_atomic_load(p, __ATOMIC_RELAXED, __HIP_MEMORY_SCOPE_AGENT); }
; __device__ __forceinline__ unsigned xb_add(unsigned* p, unsigned v) { return __hip_atomic_fetch_add(p, v, __ATOMIC_RELAXED, __HIP_MEMORY_SCOPE_AGENT); }
; #define XB_SPIN(cond, bar) do { unsigned _sp = 0; while (cond) { __builtin_amdgcn_s_sleep(1); \
;     if ((++_sp & 255u) == 0u) { if (xb_ld(&(bar)[XB_TMO])) break; if (_sp > XB_SPIN_CAP) { atomicAdd(&(bar)[XB_TMO], 1u); break; } } } } while (0)
; __device__ __forceinline__ void xcd_barrier(const XcdBarrier& b) {
;     ...
;         if (old + 1u == (gen + 1u) * nloc) {
;             __builtin_amdgcn_fence(__ATOMIC_RELEASE, "agent");
;             asm volatile("s_waitcnt vmcnt(0)" ::: "memory");
;             const unsigned og = xb_add(&bar[XB_TOP], 1u);
;             const unsigned tg = og / nx;
;             if (og + 1u == (tg + 1u) * nx) xb_add(&bar[XB_TOPGEN], 1u);
;             else XB_SPIN(xb_ld(&bar[XB_TOPGEN]) == tg, bar);
;             __builtin_amdgcn_fence(__ATOMIC_ACQUIRE, "agent");
.LBB0_1017:
	s_or_b64 exec, exec, s[18:19]
	s_waitcnt vmcnt(0)
	v_readfirstlane_b32 s2, v2
	v_cvt_f32_u32_e32 v2, v0
	v_sub_u32_e32 v3, 0, v0
	v_add_u32_e32 v1, s2, v1
	s_add_u32 s14, s4, 0x9783500
	v_rcp_iflag_f32_e32 v2, v2
	s_addc_u32 s15, s5, 0
	s_mov_b64 s[20:21], -1
	v_mul_f32_e32 v2, 0x4f7ffffe, v2
	v_cvt_u32_f32_e32 v2, v2
	v_mul_lo_u32 v3, v3, v2
	v_mul_hi_u32 v3, v2, v3
	v_add_u32_e32 v2, v2, v3
	v_mul_hi_u32 v2, v1, v2
	v_mul_lo_u32 v3, v2, v0
	v_sub_u32_e32 v3, v1, v3
	v_cmp_ge_u32_e32 vcc, v3, v0
	v_add_u32_e32 v4, 1, v2
	v_add_u32_e32 v1, 1, v1
	v_cndmask_b32_e32 v2, v2, v4, vcc
	v_sub_u32_e32 v4, v3, v0
	v_cndmask_b32_e32 v3, v3, v4, vcc
	v_cmp_ge_u32_e32 vcc, v3, v0
	v_add_u32_e32 v3, 1, v2
	s_nop 0
	v_cndmask_b32_e32 v2, v2, v3, vcc
	v_mul_lo_u32 v3, v0, v2
	v_add_u32_e32 v0, v3, v0
	v_mov_b32_e32 v7, v0
	v_cmp_ne_u32_e32 vcc, v1, v0
	v_mov_b64_e32 v[0:1], s[14:15]
	s_and_saveexec_b64 s[18:19], vcc
	s_cbranch_execz .LBB0_1029
	s_add_u32 s34, s4, 0x9783400
	s_addc_u32 s35, s5, 0
	global_load_dword v0, v65, s[34:35] sc1
	s_mov_b64 s[24:25], 0
	s_waitcnt vmcnt(0)
	v_cmp_lt_u32_e32 vcc, v0, v7
	s_and_saveexec_b64 s[22:23], vcc
	s_cbranch_execz .LBB0_1028
	s_add_u32 s20, s4, 0x9780200
	s_addc_u32 s21, s5, 0
	s_mov_b32 s2, 1
	s_mov_b64 s[4:5], 0
	s_branch .LBB0_1021

; __device__ __forceinline__ unsigned xb_ld(unsigned* p)              { return __hip_atomic_load(p, __ATOMIC_RELAXED, __HIP_MEMORY_SCOPE_AGENT); }
; #define XB_SPIN(cond, bar) do { unsigned _sp = 0; while (cond) { __builtin_amdgcn_s_sleep(1); \
;     if ((++_sp & 255u) == 0u) { if (xb_ld(&(bar)[XB_TMO])) break; if (_sp > XB_SPIN_CAP) { atomicAdd(&(bar)[XB_TMO], 1u); break; } } } } while (0)
; __device__ __forceinline__ void xcd_barrier(const XcdBarrier& b) {
;     ...
;             else XB_SPIN(xb_ld(&bar[XB_TOPGEN]) == tg, bar);
.LBB0_1023:
	global_load_dword v0, v65, s[34:35] sc1
	s_add_i32 s2, s2, 1
	s_mov_b64 s[28:29], -1
	s_waitcnt vmcnt(0)
	v_cmp_ge_u32_e32 vcc, v0, v7
	s_orn2_b64 s[26:27], vcc, exec
	s_branch .LBB0_1020

; __device__ __forceinline__ unsigned xb_ld(unsigned* p)              { return __hip_atomic_load(p, __ATOMIC_RELAXED, __HIP_MEMORY_SCOPE_AGENT); }
; __device__ __forceinline__ unsigned xb_add(unsigned* p, unsigned v) { return __hip_atomic_fetch_add(p, v, __ATOMIC_RELAXED, __HIP_MEMORY_SCOPE_AGENT); }
; #define XB_SPIN(cond, bar) do { unsigned _sp = 0; while (cond) { __builtin_amdgcn_s_sleep(1); \
;     if ((++_sp & 255u) == 0u) { if (xb_ld(&(bar)[XB_TMO])) break; if (_sp > XB_SPIN_CAP) { atomicAdd(&(bar)[XB_TMO], 1u); break; } } } } while (0)
; __device__ __forceinline__ void xcd_barrier(const XcdBarrier& b) {
;     ...
;         const unsigned old = xb_add(&bar[XB_XSUB(b.x)], 1u);
;         const unsigned gen = old / nloc;
;         if (old + 1u == (gen + 1u) * nloc) {
;             __builtin_amdgcn_fence(__ATOMIC_RELEASE, "agent");
;             asm volatile("s_waitcnt vmcnt(0)" ::: "memory");
;             const unsigned og = xb_add(&bar[XB_TOP], 1u);
;             const unsigned tg = og / nx;
;             if (og + 1u == (tg + 1u) * nx) xb_add(&bar[XB_TOPGEN], 1u);
;             else XB_SPIN(xb_ld(&bar[XB_TOPGEN]) == tg, bar);
;             __builtin_amdgcn_fence(__ATOMIC_ACQUIRE, "agent");
;             xb_add(&bar[XB_XGEN(b.x)], 1u);
;             asm volatile("s_waitcnt vmcnt(0)" ::: "memory");
;         } else {
;             XB_SPIN(xb_ld(&bar[XB_XGEN(b.x)]) == gen, bar);
;             __builtin_amdgcn_fence(__ATOMIC_ACQUIRE, "agent");
;             asm volatile("s_waitcnt vmcnt(0)" ::: "memory");
;         }
.LBB0_1138:
	s_or_b64 exec, exec, s[10:11]
	v_cvt_f32_u32_e32 v4, v2
	s_waitcnt vmcnt(0)
	v_readfirstlane_b32 s2, v3
	v_sub_u32_e32 v3, 0, v2
	v_rcp_iflag_f32_e32 v4, v4
	v_add_u32_e32 v5, s2, v1
	v_mul_f32_e32 v4, 0x4f7ffffe, v4
	v_cvt_u32_f32_e32 v4, v4
	v_mul_lo_u32 v1, v3, v4
	v_mul_hi_u32 v1, v4, v1
	v_add_u32_e32 v1, v4, v1
	v_mul_hi_u32 v1, v5, v1
	v_mul_lo_u32 v3, v1, v2
	v_sub_u32_e32 v3, v5, v3
	v_add_u32_e32 v4, 1, v1
	v_cmp_ge_u32_e32 vcc, v3, v2
	s_nop 1
	v_cndmask_b32_e32 v1, v1, v4, vcc
	v_sub_u32_e32 v4, v3, v2
	v_cndmask_b32_e32 v3, v3, v4, vcc
	v_add_u32_e32 v4, 1, v1
	v_cmp_ge_u32_e32 vcc, v3, v2
	v_add_u32_e32 v3, 1, v5
	s_nop 0
	v_cndmask_b32_e32 v1, v1, v4, vcc
	v_mul_lo_u32 v4, v2, v1
	v_add_u32_e32 v2, v4, v2
	v_cmp_ne_u32_e32 vcc, v3, v2
	s_and_saveexec_b64 s[8:9], vcc
	s_xor_b64 s[8:9], exec, s[8:9]
	s_cbranch_execz .LBB0_1152
	s_waitcnt lgkmcnt(0)
	v_add_u32_e32 v6, 1, v1
	v_mul_lo_u32 v6, v6, v0
	s_add_u32 s14, s4, 0x9783400
	s_addc_u32 s15, s5, 0
	global_load_dword v0, v65, s[14:15] sc1
	s_waitcnt vmcnt(0)
	v_cmp_lt_u32_e32 vcc, v0, v6
	s_and_saveexec_b64 s[10:11], vcc
	s_cbranch_execz .LBB0_1151
	s_add_u32 s12, s4, 0x9780200
	s_addc_u32 s13, s5, 0
	s_mov_b32 s2, 1
	s_mov_b64 s[18:19], 0
	s_branch .LBB0_1142

; __device__ __forceinline__ unsigned xb_ld(unsigned* p)              { return __hip_atomic_load(p, __ATOMIC_RELAXED, __HIP_MEMORY_SCOPE_AGENT); }
; #define XB_SPIN(cond, bar) do { unsigned _sp = 0; while (cond) { __builtin_amdgcn_s_sleep(1); \
;     if ((++_sp & 255u) == 0u) { if (xb_ld(&(bar)[XB_TMO])) break; if (_sp > XB_SPIN_CAP) { atomicAdd(&(bar)[XB_TMO], 1u); break; } } } } while (0)
; __device__ __forceinline__ void xcd_barrier(const XcdBarrier& b) {
;     ...
;             XB_SPIN(xb_ld(&bar[XB_XGEN(b.x)]) == gen, bar);
.LBB0_1144:
	global_load_dword v0, v65, s[14:15] sc1
	s_add_i32 s2, s2, 1
	s_mov_b64 s[24:25], -1
	s_waitcnt vmcnt(0)
	v_cmp_ge_u32_e32 vcc, v0, v6
	s_orn2_b64 s[22:23], vcc, exec
	s_branch .LBB0_1141

; __device__ __forceinline__ unsigned xb_ld(unsigned* p)              { return __hip_atomic_load(p, __ATOMIC_RELAXED, __HIP_MEMORY_SCOPE_AGENT); }
; __device__ __forceinline__ unsigned xb_add(unsigned* p, unsigned v) { return __hip_atomic_fetch_add(p, v, __ATOMIC_RELAXED, __HIP_MEMORY_SCOPE_AGENT); }
; #define XB_SPIN(cond, bar) do { unsigned _sp = 0; while (cond) { __builtin_amdgcn_s_sleep(1); \
;     if ((++_sp & 255u) == 0u) { if (xb_ld(&(bar)[XB_TMO])) break; if (_sp > XB_SPIN_CAP) { atomicAdd(&(bar)[XB_TMO], 1u); break; } } } } while (0)
; __device__ __forceinline__ void xcd_barrier(const XcdBarrier& b) {
;     ...
;         if (old + 1u == (gen + 1u) * nloc) {
;             __builtin_amdgcn_fence(__ATOMIC_RELEASE, "agent");
;             asm volatile("s_waitcnt vmcnt(0)" ::: "memory");
;             const unsigned og = xb_add(&bar[XB_TOP], 1u);
;             const unsigned tg = og / nx;
;             if (og + 1u == (tg + 1u) * nx) xb_add(&bar[XB_TOPGEN], 1u);
;             else XB_SPIN(xb_ld(&bar[XB_TOPGEN]) == tg, bar);
;             __builtin_amdgcn_fence(__ATOMIC_ACQUIRE, "agent");
.LBB0_1155:
	s_or_b64 exec, exec, s[12:13]
	s_waitcnt vmcnt(0)
	v_readfirstlane_b32 s2, v2
	v_cvt_f32_u32_e32 v2, v0
	v_sub_u32_e32 v3, 0, v0
	v_add_u32_e32 v1, s2, v1
	s_add_u32 s10, s4, 0x9783500
	v_rcp_iflag_f32_e32 v2, v2
	s_addc_u32 s11, s5, 0
	s_mov_b64 s[14:15], -1
	v_mul_f32_e32 v2, 0x4f7ffffe, v2
	v_cvt_u32_f32_e32 v2, v2
	v_mul_lo_u32 v3, v3, v2
	v_mul_hi_u32 v3, v2, v3
	v_add_u32_e32 v2, v2, v3
	v_mul_hi_u32 v2, v1, v2
	v_mul_lo_u32 v3, v2, v0
	v_sub_u32_e32 v3, v1, v3
	v_cmp_ge_u32_e32 vcc, v3, v0
	v_add_u32_e32 v4, 1, v2
	v_add_u32_e32 v1, 1, v1
	v_cndmask_b32_e32 v2, v2, v4, vcc
	v_sub_u32_e32 v4, v3, v0
	v_cndmask_b32_e32 v3, v3, v4, vcc
	v_cmp_ge_u32_e32 vcc, v3, v0
	v_add_u32_e32 v3, 1, v2
	s_nop 0
	v_cndmask_b32_e32 v2, v2, v3, vcc
	v_mul_lo_u32 v3, v0, v2
	v_add_u32_e32 v0, v3, v0
	v_mov_b32_e32 v7, v0
	v_cmp_ne_u32_e32 vcc, v1, v0
	v_mov_b64_e32 v[0:1], s[10:11]
	s_and_saveexec_b64 s[12:13], vcc
	s_cbranch_execz .LBB0_1167
	s_add_u32 s30, s4, 0x9783400
	s_addc_u32 s31, s5, 0
	global_load_dword v0, v65, s[30:31] sc1
	s_mov_b64 s[20:21], 0
	s_waitcnt vmcnt(0)
	v_cmp_lt_u32_e32 vcc, v0, v7
	s_and_saveexec_b64 s[18:19], vcc
	s_cbranch_execz .LBB0_1166
	s_add_u32 s14, s4, 0x9780200
	s_addc_u32 s15, s5, 0
	s_mov_b32 s2, 1
	s_mov_b64 s[4:5], 0
	s_branch .LBB0_1159

; __device__ __forceinline__ unsigned xb_ld(unsigned* p)              { return __hip_atomic_load(p, __ATOMIC_RELAXED, __HIP_MEMORY_SCOPE_AGENT); }
; __device__ __forceinline__ unsigned xb_add(unsigned* p, unsigned v) { return __hip_atomic_fetch_add(p, v, __ATOMIC_RELAXED, __HIP_MEMORY_SCOPE_AGENT); }
; #define XB_SPIN(cond, bar) do { unsigned _sp = 0; while (cond) { __builtin_amdgcn_s_sleep(1); \
;     if ((++_sp & 255u) == 0u) { if (xb_ld(&(bar)[XB_TMO])) break; if (_sp > XB_SPIN_CAP) { atomicAdd(&(bar)[XB_TMO], 1u); break; } } } } while (0)
; __device__ __forceinline__ void xcd_barrier(const XcdBarrier& b) {
;     ...
;         const unsigned old = xb_add(&bar[XB_XSUB(b.x)], 1u);
;         const unsigned gen = old / nloc;
;         if (old + 1u == (gen + 1u) * nloc) {
;             __builtin_amdgcn_fence(__ATOMIC_RELEASE, "agent");
;             asm volatile("s_waitcnt vmcnt(0)" ::: "memory");
;             const unsigned og = xb_add(&bar[XB_TOP], 1u);
;             const unsigned tg = og / nx;
;             if (og + 1u == (tg + 1u) * nx) xb_add(&bar[XB_TOPGEN], 1u);
;             else XB_SPIN(xb_ld(&bar[XB_TOPGEN]) == tg, bar);
;             __builtin_amdgcn_fence(__ATOMIC_ACQUIRE, "agent");
;             xb_add(&bar[XB_XGEN(b.x)], 1u);
;             asm volatile("s_waitcnt vmcnt(0)" ::: "memory");
;         } else {
;             XB_SPIN(xb_ld(&bar[XB_XGEN(b.x)]) == gen, bar);
;             __builtin_amdgcn_fence(__ATOMIC_ACQUIRE, "agent");
;             asm volatile("s_waitcnt vmcnt(0)" ::: "memory");
;         }
.LBB0_1228:
	s_or_b64 exec, exec, s[10:11]
	v_cvt_f32_u32_e32 v4, v2
	s_waitcnt vmcnt(0)
	v_readfirstlane_b32 s2, v3
	v_sub_u32_e32 v3, 0, v2
	v_rcp_iflag_f32_e32 v4, v4
	v_add_u32_e32 v5, s2, v1
	v_mul_f32_e32 v4, 0x4f7ffffe, v4
	v_cvt_u32_f32_e32 v4, v4
	v_mul_lo_u32 v1, v3, v4
	v_mul_hi_u32 v1, v4, v1
	v_add_u32_e32 v1, v4, v1
	v_mul_hi_u32 v1, v5, v1
	v_mul_lo_u32 v3, v1, v2
	v_sub_u32_e32 v3, v5, v3
	v_add_u32_e32 v4, 1, v1
	v_cmp_ge_u32_e32 vcc, v3, v2
	s_nop 1
	v_cndmask_b32_e32 v1, v1, v4, vcc
	v_sub_u32_e32 v4, v3, v2
	v_cndmask_b32_e32 v3, v3, v4, vcc
	v_add_u32_e32 v4, 1, v1
	v_cmp_ge_u32_e32 vcc, v3, v2
	v_add_u32_e32 v3, 1, v5
	s_nop 0
	v_cndmask_b32_e32 v1, v1, v4, vcc
	v_mul_lo_u32 v4, v2, v1
	v_add_u32_e32 v2, v4, v2
	v_cmp_ne_u32_e32 vcc, v3, v2
	s_and_saveexec_b64 s[8:9], vcc
	s_xor_b64 s[8:9], exec, s[8:9]
	s_cbranch_execz .LBB0_1242
	s_waitcnt lgkmcnt(0)
	v_add_u32_e32 v6, 1, v1
	v_mul_lo_u32 v6, v6, v0
	s_add_u32 s14, s4, 0x9783400
	s_addc_u32 s15, s5, 0
	global_load_dword v0, v65, s[14:15] sc1
	s_waitcnt vmcnt(0)
	v_cmp_lt_u32_e32 vcc, v0, v6
	s_and_saveexec_b64 s[10:11], vcc
	s_cbranch_execz .LBB0_1241
	s_add_u32 s12, s4, 0x9780200
	s_addc_u32 s13, s5, 0
	s_mov_b32 s2, 1
	s_mov_b64 s[16:17], 0
	s_branch .LBB0_1232

; __device__ __forceinline__ unsigned xb_ld(unsigned* p)              { return __hip_atomic_load(p, __ATOMIC_RELAXED, __HIP_MEMORY_SCOPE_AGENT); }
; #define XB_SPIN(cond, bar) do { unsigned _sp = 0; while (cond) { __builtin_amdgcn_s_sleep(1); \
;     if ((++_sp & 255u) == 0u) { if (xb_ld(&(bar)[XB_TMO])) break; if (_sp > XB_SPIN_CAP) { atomicAdd(&(bar)[XB_TMO], 1u); break; } } } } while (0)
; __device__ __forceinline__ void xcd_barrier(const XcdBarrier& b) {
;     ...
;             XB_SPIN(xb_ld(&bar[XB_XGEN(b.x)]) == gen, bar);
.LBB0_1234:
	global_load_dword v0, v65, s[14:15] sc1
	s_add_i32 s2, s2, 1
	s_mov_b64 s[22:23], -1
	s_waitcnt vmcnt(0)
	v_cmp_ge_u32_e32 vcc, v0, v6
	s_orn2_b64 s[20:21], vcc, exec
	s_branch .LBB0_1231

; __device__ __forceinline__ unsigned xb_ld(unsigned* p)              { return __hip_atomic_load(p, __ATOMIC_RELAXED, __HIP_MEMORY_SCOPE_AGENT); }
; __device__ __forceinline__ unsigned xb_add(unsigned* p, unsigned v) { return __hip_atomic_fetch_add(p, v, __ATOMIC_RELAXED, __HIP_MEMORY_SCOPE_AGENT); }
; #define XB_SPIN(cond, bar) do { unsigned _sp = 0; while (cond) { __builtin_amdgcn_s_sleep(1); \
;     if ((++_sp & 255u) == 0u) { if (xb_ld(&(bar)[XB_TMO])) break; if (_sp > XB_SPIN_CAP) { atomicAdd(&(bar)[XB_TMO], 1u); break; } } } } while (0)
; __device__ __forceinline__ void xcd_barrier(const XcdBarrier& b) {
;     ...
;         if (old + 1u == (gen + 1u) * nloc) {
;             __builtin_amdgcn_fence(__ATOMIC_RELEASE, "agent");
;             asm volatile("s_waitcnt vmcnt(0)" ::: "memory");
;             const unsigned og = xb_add(&bar[XB_TOP], 1u);
;             const unsigned tg = og / nx;
;             if (og + 1u == (tg + 1u) * nx) xb_add(&bar[XB_TOPGEN], 1u);
;             else XB_SPIN(xb_ld(&bar[XB_TOPGEN]) == tg, bar);
;             __builtin_amdgcn_fence(__ATOMIC_ACQUIRE, "agent");
.LBB0_1245:
	s_or_b64 exec, exec, s[12:13]
	s_waitcnt vmcnt(0)
	v_readfirstlane_b32 s2, v2
	v_cvt_f32_u32_e32 v2, v0
	v_sub_u32_e32 v3, 0, v0
	v_add_u32_e32 v1, s2, v1
	s_add_u32 s10, s4, 0x9783500
	v_rcp_iflag_f32_e32 v2, v2
	s_addc_u32 s11, s5, 0
	s_mov_b64 s[14:15], -1
	v_mul_f32_e32 v2, 0x4f7ffffe, v2
	v_cvt_u32_f32_e32 v2, v2
	v_mul_lo_u32 v3, v3, v2
	v_mul_hi_u32 v3, v2, v3
	v_add_u32_e32 v2, v2, v3
	v_mul_hi_u32 v2, v1, v2
	v_mul_lo_u32 v3, v2, v0
	v_sub_u32_e32 v3, v1, v3
	v_cmp_ge_u32_e32 vcc, v3, v0
	v_add_u32_e32 v4, 1, v2
	v_add_u32_e32 v1, 1, v1
	v_cndmask_b32_e32 v2, v2, v4, vcc
	v_sub_u32_e32 v4, v3, v0
	v_cndmask_b32_e32 v3, v3, v4, vcc
	v_cmp_ge_u32_e32 vcc, v3, v0
	v_add_u32_e32 v3, 1, v2
	s_nop 0
	v_cndmask_b32_e32 v2, v2, v3, vcc
	v_mul_lo_u32 v3, v0, v2
	v_add_u32_e32 v0, v3, v0
	v_mov_b32_e32 v7, v0
	v_cmp_ne_u32_e32 vcc, v1, v0
	v_mov_b64_e32 v[0:1], s[10:11]
	s_and_saveexec_b64 s[12:13], vcc
	s_cbranch_execz .LBB0_1257
	s_add_u32 s30, s4, 0x9783400
	s_addc_u32 s31, s5, 0
	global_load_dword v0, v65, s[30:31] sc1
	s_mov_b64 s[18:19], 0
	s_waitcnt vmcnt(0)
	v_cmp_lt_u32_e32 vcc, v0, v7
	s_and_saveexec_b64 s[16:17], vcc
	s_cbranch_execz .LBB0_1256
	s_add_u32 s14, s4, 0x9780200
	s_addc_u32 s15, s5, 0
	s_mov_b32 s2, 1
	s_mov_b64 s[4:5], 0
	s_branch .LBB0_1249

; __device__ __forceinline__ unsigned xb_ld(unsigned* p)              { return __hip_atomic_load(p, __ATOMIC_RELAXED, __HIP_MEMORY_SCOPE_AGENT); }
; #define XB_SPIN(cond, bar) do { unsigned _sp = 0; while (cond) { __builtin_amdgcn_s_sleep(1); \
;     if ((++_sp & 255u) == 0u) { if (xb_ld(&(bar)[XB_TMO])) break; if (_sp > XB_SPIN_CAP) { atomicAdd(&(bar)[XB_TMO], 1u); break; } } } } while (0)
; __device__ __forceinline__ void xcd_barrier(const XcdBarrier& b) {
;     ...
;             else XB_SPIN(xb_ld(&bar[XB_TOPGEN]) == tg, bar);
.LBB0_1251:
	global_load_dword v0, v65, s[30:31] sc1
	s_add_i32 s2, s2, 1
	s_mov_b64 s[22:23], -1
	s_waitcnt vmcnt(0)
	v_cmp_ge_u32_e32 vcc, v0, v7
	s_orn2_b64 s[20:21], vcc, exec
	s_branch .LBB0_1248
